# P3 sample attention loop: V fragment reads hoisted, permlane running max, bpermute waits removed
# baseline (speedup 1.0000x reference)
.LBB0_1719:
	v_add_u32_e32 v62, v64, v77
	ds_read_b128 v[58:61], v62
	ds_read_b128 v[106:109], v62 offset:64
	v_and_b32_e32 v63, v80, v99
	v_and_b32_e32 v82, v80, v100
	v_and_b32_e32 v83, v81, v94
	s_cmp_lt_u32 s60, 64
	s_cselect_b64 s[66:67], -1, 0
	s_waitcnt lgkmcnt(1)
	v_mfma_f32_16x16x32_bf16 v[58:61], v[58:61], v[0:3], 0
	ds_read_b128 v[110:113], v62 offset:2624
	ds_read_b128 v[114:117], v62 offset:5184
	ds_read_b128 v[118:121], v62 offset:7744
	s_waitcnt lgkmcnt(3)
	v_mfma_f32_16x16x32_bf16 v[58:61], v[106:109], v[4:7], v[58:61]
	ds_read_b128 v[106:109], v62 offset:2560
	s_waitcnt lgkmcnt(0)
	v_mfma_f32_16x16x32_bf16 v[106:109], v[106:109], v[0:3], 0
	v_mfma_f32_16x16x32_bf16 v[106:109], v[110:113], v[4:7], v[106:109]
	ds_read_b128 v[110:113], v62 offset:5120
	s_waitcnt lgkmcnt(0)
	v_mfma_f32_16x16x32_bf16 v[110:113], v[110:113], v[0:3], 0
	v_mfma_f32_16x16x32_bf16 v[110:113], v[114:117], v[4:7], v[110:113]
	ds_read_b128 v[114:117], v62 offset:7680
	v_and_b32_e32 v62, v80, v94
	v_cmp_ne_u32_e32 vcc, 0, v62
	v_and_b32_e32 v62, v80, v95
	s_waitcnt lgkmcnt(0)
	ds_read_b64_tr_b16 v[140:141], v93
	ds_read_b64_tr_b16 v[144:145], v93 offset:32
	ds_read_b64_tr_b16 v[148:149], v93 offset:64
	ds_read_b64_tr_b16 v[152:153], v93 offset:96
	ds_read_b64_tr_b16 v[142:143], v93 offset:2560
	ds_read_b64_tr_b16 v[146:147], v93 offset:2592
	ds_read_b64_tr_b16 v[150:151], v93 offset:2624
	ds_read_b64_tr_b16 v[154:155], v93 offset:2656
	ds_read_b64_tr_b16 v[156:157], v102
	ds_read_b64_tr_b16 v[160:161], v102 offset:32
	ds_read_b64_tr_b16 v[164:165], v102 offset:64
	ds_read_b64_tr_b16 v[168:169], v102 offset:96
	ds_read_b64_tr_b16 v[158:159], v102 offset:2560
	ds_read_b64_tr_b16 v[162:163], v102 offset:2592
	ds_read_b64_tr_b16 v[166:167], v102 offset:2624
	ds_read_b64_tr_b16 v[170:171], v102 offset:2656
	v_mfma_f32_16x16x32_bf16 v[114:117], v[114:117], v[0:3], 0
	v_cndmask_b32_e32 v58, v86, v58, vcc
	v_cmp_ne_u32_e32 vcc, 0, v62
	v_and_b32_e32 v62, v80, v96
	v_mfma_f32_16x16x32_bf16 v[114:117], v[118:121], v[4:7], v[114:117]
	v_cndmask_b32_e32 v59, v86, v59, vcc
	v_cmp_ne_u32_e32 vcc, 0, v62
	v_and_b32_e32 v62, v80, v97
	s_nop 0
	v_cndmask_b32_e32 v60, v86, v60, vcc
	v_cmp_ne_u32_e32 vcc, 0, v62
	v_and_b32_e32 v62, v80, v98
	v_and_b32_e32 v80, v80, v101
	v_cndmask_b32_e32 v61, v86, v61, vcc
	v_cmp_ne_u32_e32 vcc, 0, v62
	s_nop 1
	v_cndmask_b32_e32 v62, v86, v106, vcc
	v_cmp_ne_u32_e32 vcc, 0, v63
	s_nop 1
	v_cndmask_b32_e32 v63, v86, v107, vcc
	v_cmp_ne_u32_e32 vcc, 0, v82
	s_nop 1
	v_cndmask_b32_e32 v82, v86, v108, vcc
	v_cmp_ne_u32_e32 vcc, 0, v80
	s_nop 1
	v_cndmask_b32_e32 v80, v86, v109, vcc
	v_cmp_ne_u32_e32 vcc, 0, v83
	v_and_b32_e32 v83, v81, v95
	v_cmp_ne_u32_e64 s[0:1], 0, v83
	v_and_b32_e32 v83, v81, v96
	v_cmp_ne_u32_e64 s[2:3], 0, v83
	s_and_b64 s[2:3], s[66:67], s[2:3]
	v_and_b32_e32 v83, v81, v97
	v_cndmask_b32_e64 v109, v86, v112, s[2:3]
	v_max3_f32 v112, v58, s80, v59
	v_cmp_ne_u32_e64 s[4:5], 0, v83
	v_and_b32_e32 v83, v81, v98
	v_max3_f32 v112, v112, v60, v61
	v_cmp_ne_u32_e64 s[6:7], 0, v83
	v_and_b32_e32 v83, v81, v99
	s_and_b64 s[0:1], s[66:67], s[0:1]
	s_and_b64 vcc, s[66:67], vcc
	v_max3_f32 v112, v112, v62, v63
	v_cmp_ne_u32_e64 s[12:13], 0, v83
	v_and_b32_e32 v83, v81, v100
	v_and_b32_e32 v81, v81, v101
	s_and_b64 s[4:5], s[66:67], s[4:5]
	v_cndmask_b32_e64 v111, v86, v111, s[0:1]
	v_cndmask_b32_e32 v110, v86, v110, vcc
	v_max3_f32 v112, v112, v82, v80
	v_cmp_ne_u32_e64 s[14:15], 0, v83
	v_cmp_ne_u32_e64 s[16:17], 0, v81
	s_and_b64 s[12:13], s[66:67], s[12:13]
	s_and_b64 s[6:7], s[66:67], s[6:7]
	v_cndmask_b32_e64 v108, v86, v113, s[4:5]
	v_max3_f32 v112, v112, v110, v111
	s_and_b64 s[16:17], s[66:67], s[16:17]
	s_and_b64 s[14:15], s[66:67], s[14:15]
	v_cndmask_b32_e64 v106, v86, v115, s[12:13]
	v_cndmask_b32_e64 v107, v86, v114, s[6:7]
	v_max3_f32 v112, v112, v109, v108
	v_cmp_lt_i32_e32 vcc, v87, v88
	v_cndmask_b32_e64 v81, v86, v117, s[16:17]
	v_cndmask_b32_e64 v83, v86, v116, s[14:15]
	v_max3_f32 v112, v112, v107, v106
	v_cndmask_b32_e32 v113, v133, v87, vcc
	v_max3_f32 v112, v112, v83, v81
	v_lshlrev_b32_e32 v113, 2, v113
	v_cmp_lt_i32_e32 vcc, v89, v88
	v_mov_b32_e32 v113, v112
	s_nop 1
	v_permlane16_swap_b32_e32 v113, v112
	v_max_f32_e32 v112, v112, v113
	v_cndmask_b32_e32 v113, v133, v89, vcc
	v_lshlrev_b32_e32 v113, 2, v113
	v_mov_b32_e32 v113, v112
	s_nop 1
	v_permlane32_swap_b32_e32 v113, v112
	v_max3_f32 v116, v105, v112, v113
	v_cmp_neq_f32_e32 vcc, s80, v116
	s_nop 1
	v_cndmask_b32_e32 v112, 0, v116, vcc
	v_sub_f32_e32 v58, v58, v112
	v_exp_f32_e32 v113, v58
	v_sub_f32_e32 v59, v59, v112
	v_exp_f32_e32 v59, v59
	v_sub_f32_e32 v60, v60, v112
	v_exp_f32_e32 v60, v60
	v_sub_f32_e32 v61, v61, v112
	v_exp_f32_e32 v61, v61
	v_sub_f32_e32 v62, v62, v112
	v_add_f32_e32 v58, 0, v113
	v_exp_f32_e32 v62, v62
	v_sub_f32_e32 v63, v63, v112
	v_add_f32_e32 v58, v59, v58
	v_exp_f32_e32 v63, v63
	v_sub_f32_e32 v82, v82, v112
	v_add_f32_e32 v58, v60, v58
	v_exp_f32_e32 v82, v82
	v_sub_f32_e32 v80, v80, v112
	v_add_f32_e32 v58, v61, v58
	v_exp_f32_e32 v80, v80
	v_sub_f32_e32 v110, v110, v112
	v_add_f32_e32 v58, v62, v58
	v_exp_f32_e32 v117, v110
	v_sub_f32_e32 v110, v111, v112
	v_add_f32_e32 v58, v63, v58
	v_exp_f32_e32 v118, v110
	v_sub_f32_e32 v109, v109, v112
	v_add_f32_e32 v58, v82, v58
	v_exp_f32_e32 v119, v109
	v_sub_f32_e32 v108, v108, v112
	v_add_f32_e32 v58, v80, v58
	v_exp_f32_e32 v120, v108
	v_sub_f32_e32 v107, v107, v112
	v_add_f32_e32 v58, v117, v58
	v_exp_f32_e32 v121, v107
	v_sub_f32_e32 v106, v106, v112
	v_add_f32_e32 v58, v118, v58
	v_exp_f32_e32 v122, v106
	v_sub_f32_e32 v83, v83, v112
	v_add_f32_e32 v58, v119, v58
	v_exp_f32_e32 v123, v83
	v_sub_f32_e32 v81, v81, v112
	v_add_f32_e32 v58, v120, v58
	v_exp_f32_e32 v124, v81
	v_add_f32_e32 v58, v121, v58
	v_add_f32_e32 v58, v122, v58
	v_sub_f32_e32 v105, v105, v112
	v_add_f32_e32 v58, v123, v58
	v_add_f32_e32 v125, v124, v58
	v_exp_f32_e32 v58, v105
	s_nop 0
	v_pk_mul_f32 v[54:55], v[54:55], v[58:59] op_sel_hi:[1,0]
	v_pk_mul_f32 v[52:53], v[52:53], v[58:59] op_sel_hi:[1,0]
	v_pk_mul_f32 v[46:47], v[46:47], v[58:59] op_sel_hi:[1,0]
	v_pk_mul_f32 v[44:45], v[44:45], v[58:59] op_sel_hi:[1,0]
	v_pk_mul_f32 v[50:51], v[50:51], v[58:59] op_sel_hi:[1,0]
	v_pk_mul_f32 v[48:49], v[48:49], v[58:59] op_sel_hi:[1,0]
	v_pk_mul_f32 v[42:43], v[42:43], v[58:59] op_sel_hi:[1,0]
	v_pk_mul_f32 v[40:41], v[40:41], v[58:59] op_sel_hi:[1,0]
	v_fmac_f32_e32 v125, v104, v58
	v_cvt_pk_bf16_f32 v58, v113, v59
	v_cvt_pk_bf16_f32 v59, v60, v61
	v_cvt_pk_bf16_f32 v60, v62, v63
	v_cvt_pk_bf16_f32 v61, v82, v80
	s_waitcnt lgkmcnt(0)
	s_nop 0
	v_mfma_f32_16x16x32_bf16 v[52:55], v[140:143], v[58:61], v[52:55]
	v_mfma_f32_16x16x32_bf16 v[44:47], v[144:147], v[58:61], v[44:47]
	v_mfma_f32_16x16x32_bf16 v[48:51], v[148:151], v[58:61], v[48:51]
	v_mfma_f32_16x16x32_bf16 v[40:43], v[152:155], v[58:61], v[40:43]
	v_cvt_pk_bf16_f32 v58, v117, v118
	v_cvt_pk_bf16_f32 v59, v119, v120
	v_cvt_pk_bf16_f32 v60, v121, v122
	v_cvt_pk_bf16_f32 v61, v123, v124
	s_waitcnt lgkmcnt(0)
	s_nop 0
	v_mfma_f32_16x16x32_bf16 v[52:55], v[156:159], v[58:61], v[52:55]
	v_mfma_f32_16x16x32_bf16 v[44:47], v[160:163], v[58:61], v[44:47]
	v_mfma_f32_16x16x32_bf16 v[48:51], v[164:167], v[58:61], v[48:51]
	v_mov_b32_e32 v105, v116
	v_mov_b32_e32 v104, v125
	v_mfma_f32_16x16x32_bf16 v[40:43], v[168:171], v[58:61], v[40:43]
	s_or_b64 exec, exec, s[62:63]
	s_andn2_b64 vcc, exec, s[26:27]
	s_cbranch_vccz .LBB0_1715

.LBB0_1723:
	v_add_u32_e32 v62, v64, v77
	ds_read_b128 v[58:61], v62
	ds_read_b128 v[106:109], v62 offset:64
	ds_read_b128 v[110:113], v62 offset:2560
	ds_read_b128 v[114:117], v62 offset:2624
	ds_read_b128 v[118:121], v62 offset:5120
	v_and_b32_e32 v63, v56, v94
	s_waitcnt lgkmcnt(4)
	v_mfma_f32_16x16x32_bf16 v[58:61], v[58:61], v[0:3], 0
	v_and_b32_e32 v82, v56, v95
	v_cmp_ne_u32_e32 vcc, 0, v63
	s_waitcnt lgkmcnt(2)
	v_mfma_f32_16x16x32_bf16 v[110:113], v[110:113], v[0:3], 0
	v_mfma_f32_16x16x32_bf16 v[58:61], v[106:109], v[4:7], v[58:61]
	ds_read_b128 v[106:109], v62 offset:5184
	s_waitcnt lgkmcnt(2)
	v_mfma_f32_16x16x32_bf16 v[110:113], v[114:117], v[4:7], v[110:113]
	ds_read_b128 v[114:117], v62 offset:7680
	ds_read_b128 v[122:125], v62 offset:7744
	s_nop 2
	v_cndmask_b32_e32 v62, v86, v58, vcc
	v_cmp_ne_u32_e32 vcc, 0, v82
	s_waitcnt lgkmcnt(3)
	v_mfma_f32_16x16x32_bf16 v[118:121], v[118:121], v[0:3], 0
	v_and_b32_e32 v58, v56, v96
	v_cndmask_b32_e32 v63, v86, v59, vcc
	v_cmp_ne_u32_e32 vcc, 0, v58
	s_waitcnt lgkmcnt(1)
	v_mfma_f32_16x16x32_bf16 v[114:117], v[114:117], v[0:3], 0
	v_and_b32_e32 v58, v56, v97
	v_cndmask_b32_e32 v82, v86, v60, vcc
	v_cmp_ne_u32_e32 vcc, 0, v58
	v_mfma_f32_16x16x32_bf16 v[106:109], v[106:109], v[4:7], v[118:121]
	s_nop 0
	v_cndmask_b32_e32 v83, v86, v61, vcc
	s_nop 0
	v_and_b32_e32 v118, v56, v98
	s_waitcnt lgkmcnt(0)
	ds_read_b64_tr_b16 v[140:141], v93
	ds_read_b64_tr_b16 v[144:145], v93 offset:32
	ds_read_b64_tr_b16 v[148:149], v93 offset:64
	ds_read_b64_tr_b16 v[152:153], v93 offset:96
	ds_read_b64_tr_b16 v[142:143], v93 offset:2560
	ds_read_b64_tr_b16 v[146:147], v93 offset:2592
	ds_read_b64_tr_b16 v[150:151], v93 offset:2624
	ds_read_b64_tr_b16 v[154:155], v93 offset:2656
	ds_read_b64_tr_b16 v[156:157], v102
	ds_read_b64_tr_b16 v[160:161], v102 offset:32
	ds_read_b64_tr_b16 v[164:165], v102 offset:64
	ds_read_b64_tr_b16 v[168:169], v102 offset:96
	ds_read_b64_tr_b16 v[158:159], v102 offset:2560
	ds_read_b64_tr_b16 v[162:163], v102 offset:2592
	ds_read_b64_tr_b16 v[166:167], v102 offset:2624
	ds_read_b64_tr_b16 v[170:171], v102 offset:2656
	v_mfma_f32_16x16x32_bf16 v[58:61], v[122:125], v[4:7], v[114:117]
	v_cmp_ne_u32_e32 vcc, 0, v118
	s_nop 1
	v_and_b32_e32 v114, v56, v99
	v_cndmask_b32_e32 v110, v86, v110, vcc
	v_cmp_ne_u32_e32 vcc, 0, v114
	v_and_b32_e32 v114, v56, v100
	v_and_b32_e32 v56, v56, v101
	v_cndmask_b32_e32 v111, v86, v111, vcc
	v_cmp_ne_u32_e32 vcc, 0, v114
	s_nop 1
	v_cndmask_b32_e32 v112, v86, v112, vcc
	v_cmp_ne_u32_e32 vcc, 0, v56
	s_nop 1
	v_cndmask_b32_e32 v56, v86, v113, vcc
	v_and_b32_e32 v113, v57, v94
	v_cmp_ne_u32_e32 vcc, 0, v113
	v_and_b32_e32 v113, v57, v95
	s_nop 0
	v_cndmask_b32_e32 v106, v86, v106, vcc
	v_cmp_ne_u32_e32 vcc, 0, v113
	v_and_b32_e32 v113, v57, v96
	s_nop 0
	v_cndmask_b32_e32 v107, v86, v107, vcc
	v_cmp_ne_u32_e32 vcc, 0, v113
	v_and_b32_e32 v113, v57, v97
	s_nop 0
	v_cndmask_b32_e32 v108, v86, v108, vcc
	v_cmp_ne_u32_e32 vcc, 0, v113
	v_and_b32_e32 v113, v57, v98
	s_nop 0
	v_cndmask_b32_e32 v109, v86, v109, vcc
	v_cmp_ne_u32_e32 vcc, 0, v113
	v_and_b32_e32 v113, v57, v99
	s_nop 0
	v_cndmask_b32_e32 v58, v86, v58, vcc
	v_cmp_ne_u32_e32 vcc, 0, v113
	v_and_b32_e32 v113, v57, v100
	v_and_b32_e32 v57, v57, v101
	v_cndmask_b32_e32 v59, v86, v59, vcc
	v_cmp_ne_u32_e32 vcc, 0, v113
	s_nop 1
	v_cndmask_b32_e32 v60, v86, v60, vcc
	v_cmp_ne_u32_e32 vcc, 0, v57
	v_max3_f32 v57, v62, s80, v63
	v_max3_f32 v57, v57, v82, v83
	v_max3_f32 v57, v57, v110, v111
	v_max3_f32 v57, v57, v112, v56
	v_max3_f32 v57, v57, v106, v107
	v_cndmask_b32_e32 v118, v86, v61, vcc
	v_max3_f32 v57, v57, v108, v109
	v_cmp_lt_i32_e32 vcc, v87, v88
	v_max3_f32 v57, v57, v58, v59
	v_max3_f32 v57, v57, v60, v118
	v_cndmask_b32_e32 v61, v133, v87, vcc
	v_lshlrev_b32_e32 v61, 2, v61
	v_cmp_lt_i32_e32 vcc, v89, v88
	v_mov_b32_e32 v61, v57
	s_nop 1
	v_permlane16_swap_b32_e32 v61, v57
	v_max_f32_e32 v57, v57, v61
	v_cndmask_b32_e32 v61, v133, v89, vcc
	v_lshlrev_b32_e32 v61, 2, v61
	v_mov_b32_e32 v61, v57
	s_nop 1
	v_permlane32_swap_b32_e32 v61, v57
	v_max3_f32 v119, v105, v57, v61
	v_cmp_neq_f32_e32 vcc, s80, v119
	s_nop 1
	v_cndmask_b32_e32 v120, 0, v119, vcc
	v_sub_f32_e32 v61, v62, v120
	v_exp_f32_e32 v61, v61
	v_sub_f32_e32 v62, v63, v120
	v_exp_f32_e32 v62, v62
	v_sub_f32_e32 v63, v82, v120
	v_exp_f32_e32 v63, v63
	v_sub_f32_e32 v82, v83, v120
	v_sub_f32_e32 v57, v105, v120
	v_exp_f32_e32 v83, v82
	v_sub_f32_e32 v105, v110, v120
	v_add_f32_e32 v82, 0, v61
	v_exp_f32_e32 v105, v105
	v_sub_f32_e32 v110, v111, v120
	v_add_f32_e32 v82, v62, v82
	v_exp_f32_e32 v110, v110
	v_sub_f32_e32 v111, v112, v120
	v_add_f32_e32 v82, v63, v82
	v_exp_f32_e32 v111, v111
	v_sub_f32_e32 v56, v56, v120
	v_add_f32_e32 v82, v83, v82
	v_exp_f32_e32 v112, v56
	v_add_f32_e32 v56, v105, v82
	v_add_f32_e32 v56, v110, v56
	v_add_f32_e32 v56, v111, v56
	v_add_f32_e32 v121, v112, v56
	v_sub_f32_e32 v56, v106, v120
	v_exp_f32_e32 v82, v57
	v_exp_f32_e32 v122, v56
	v_sub_f32_e32 v56, v107, v120
	v_exp_f32_e32 v123, v56
	v_sub_f32_e32 v56, v108, v120
	v_exp_f32_e32 v124, v56
	v_sub_f32_e32 v56, v109, v120
	v_sub_f32_e32 v128, v60, v120
	v_exp_f32_e32 v125, v56
	v_sub_f32_e32 v56, v58, v120
	v_pk_mul_f32 v[54:55], v[54:55], v[82:83] op_sel_hi:[1,0]
	v_pk_mul_f32 v[52:53], v[52:53], v[82:83] op_sel_hi:[1,0]
	v_cvt_pk_bf16_f32 v57, v63, v83
	v_exp_f32_e32 v83, v128
	v_exp_f32_e32 v126, v56
	v_sub_f32_e32 v56, v59, v120
	v_exp_f32_e32 v127, v56
	v_cvt_pk_bf16_f32 v56, v61, v62
	v_cvt_pk_bf16_f32 v58, v105, v110
	v_cvt_pk_bf16_f32 v59, v111, v112
	s_waitcnt lgkmcnt(0)
	v_pk_mul_f32 v[46:47], v[46:47], v[82:83] op_sel_hi:[1,0]
	v_mfma_f32_16x16x32_bf16 v[52:55], v[140:143], v[56:59], v[52:55]
	v_mul_f32_e64 v44, v44, v82
	v_mul_f32_e64 v45, v45, v82
	v_pk_mul_f32 v[50:51], v[50:51], v[82:83] op_sel_hi:[1,0]
	v_pk_mul_f32 v[48:49], v[48:49], v[82:83] op_sel_hi:[1,0]
	v_pk_mul_f32 v[42:43], v[42:43], v[82:83] op_sel_hi:[1,0]
	v_pk_mul_f32 v[40:41], v[40:41], v[82:83] op_sel_hi:[1,0]
	v_mfma_f32_16x16x32_bf16 v[44:47], v[144:147], v[56:59], v[44:47]
	v_sub_f32_e32 v105, v118, v120
	v_exp_f32_e32 v105, v105
	v_mfma_f32_16x16x32_bf16 v[48:51], v[148:151], v[56:59], v[48:51]
	v_mfma_f32_16x16x32_bf16 v[40:43], v[152:155], v[56:59], v[40:43]
	s_waitcnt lgkmcnt(0)
	v_cvt_pk_bf16_f32 v56, v122, v123
	v_cvt_pk_bf16_f32 v57, v124, v125
	v_cvt_pk_bf16_f32 v58, v126, v127
	v_cvt_pk_bf16_f32 v59, v83, v105
	s_nop 0
	v_mfma_f32_16x16x32_bf16 v[52:55], v[156:159], v[56:59], v[52:55]
	v_add_f32_e32 v114, v122, v121
	v_add_f32_e32 v114, v123, v114
	v_add_f32_e32 v114, v124, v114
	v_mfma_f32_16x16x32_bf16 v[44:47], v[160:163], v[56:59], v[44:47]
	v_add_f32_e32 v110, v125, v114
	v_add_f32_e32 v110, v126, v110
	v_add_f32_e32 v110, v127, v110
	v_mfma_f32_16x16x32_bf16 v[48:51], v[164:167], v[56:59], v[48:51]
	v_add_f32_e32 v83, v83, v110
	v_add_f32_e32 v83, v105, v83
	v_fmac_f32_e32 v83, v104, v82
	v_mfma_f32_16x16x32_bf16 v[40:43], v[168:171], v[56:59], v[40:43]
	v_mov_b32_e32 v104, v83
	v_mov_b32_e32 v105, v119
	s_branch .LBB0_1700
